# v6 + P8 gather loop unrolled x4 and software-pipelined by one row group (second register bank for odd groups)
# baseline (speedup 1.0000x reference)
.LBB0_1546:
	v_mov_b32_e32 v102, s5
	ds_read_b128 v[98:101], v102
	ds_read_b128 v[102:105], v102 offset:16
	s_waitcnt lgkmcnt(1)
	v_readfirstlane_b32 s12, v98
	s_addk_i32 s12, 0x800
	s_lshl_b32 s21, s12, 2
	s_ashr_i32 s13, s12, 31
	s_add_i32 s21, s21, 0
	s_add_u32 s12, s12, s3
	s_addc_u32 s13, s13, 0
	v_mov_b32_e32 v98, s21
	s_lshl_b64 s[12:13], s[12:13], 11
	ds_read_b32 v125, v98 offset:24576
	v_lshl_add_u64 v[98:99], v[146:147], 0, s[12:13]
	global_load_dwordx4 v[126:129], v[98:99], off offset:16
	global_load_dwordx4 v[156:159], v[98:99], off
	v_readfirstlane_b32 s19, v100
	s_addk_i32 s19, 0x800
	s_lshl_b32 s12, s19, 2
	s_ashr_i32 s13, s19, 31
	s_add_i32 s12, s12, 0
	v_mov_b32_e32 v98, s12
	s_add_u32 s12, s19, s3
	s_addc_u32 s13, s13, 0
	s_lshl_b64 s[12:13], s[12:13], 11
	ds_read_b32 v124, v98 offset:24576
	v_lshl_add_u64 v[98:99], v[146:147], 0, s[12:13]
	global_load_dwordx4 v[114:117], v[98:99], off offset:16
	global_load_dwordx4 v[118:121], v[98:99], off
	s_waitcnt lgkmcnt(2)
	v_readfirstlane_b32 s12, v102
	s_addk_i32 s12, 0x800
	s_lshl_b32 s21, s12, 2
	s_ashr_i32 s13, s12, 31
	s_add_i32 s21, s21, 0
	s_add_u32 s12, s12, s3
	s_addc_u32 s13, s13, 0
	v_mov_b32_e32 v98, s21
	s_lshl_b64 s[12:13], s[12:13], 11
	ds_read_b32 v123, v98 offset:24576
	v_lshl_add_u64 v[98:99], v[146:147], 0, s[12:13]
	global_load_dwordx4 v[106:109], v[98:99], off offset:16
	global_load_dwordx4 v[110:113], v[98:99], off
	v_readfirstlane_b32 s19, v104
	s_addk_i32 s19, 0x800
	s_lshl_b32 s12, s19, 2
	s_ashr_i32 s13, s19, 31
	s_add_i32 s12, s12, 0
	v_mov_b32_e32 v98, s12
	s_add_u32 s12, s19, s3
	s_addc_u32 s13, s13, 0
	s_lshl_b64 s[12:13], s[12:13], 11
	v_lshl_add_u64 v[102:103], v[146:147], 0, s[12:13]
	ds_read_b32 v122, v98 offset:24576
	global_load_dwordx4 v[98:101], v[102:103], off offset:16
	s_nop 0
	global_load_dwordx4 v[102:105], v[102:103], off
	s_add_i32 s5, s5, 32
	v_mov_b32_e32 v204, s5
	ds_read_b128 v[200:203], v204
	ds_read_b128 v[204:207], v204 offset:16
	s_waitcnt lgkmcnt(1)
	v_readfirstlane_b32 s12, v200
	s_addk_i32 s12, 0x800
	s_lshl_b32 s21, s12, 2
	s_ashr_i32 s13, s12, 31
	s_add_i32 s21, s21, 0
	s_add_u32 s12, s12, s3
	s_addc_u32 s13, s13, 0
	v_mov_b32_e32 v200, s21
	s_lshl_b64 s[12:13], s[12:13], 11
	ds_read_b32 v227, v200 offset:24576
	v_lshl_add_u64 v[200:201], v[146:147], 0, s[12:13]
	global_load_dwordx4 v[228:231], v[200:201], off offset:16
	global_load_dwordx4 v[232:235], v[200:201], off
	v_readfirstlane_b32 s19, v202
	s_addk_i32 s19, 0x800
	s_lshl_b32 s12, s19, 2
	s_ashr_i32 s13, s19, 31
	s_add_i32 s12, s12, 0
	v_mov_b32_e32 v200, s12
	s_add_u32 s12, s19, s3
	s_addc_u32 s13, s13, 0
	s_lshl_b64 s[12:13], s[12:13], 11
	ds_read_b32 v226, v200 offset:24576
	v_lshl_add_u64 v[200:201], v[146:147], 0, s[12:13]
	global_load_dwordx4 v[216:219], v[200:201], off offset:16
	global_load_dwordx4 v[220:223], v[200:201], off
	s_waitcnt lgkmcnt(2)
	v_readfirstlane_b32 s12, v204
	s_addk_i32 s12, 0x800
	s_lshl_b32 s21, s12, 2
	s_ashr_i32 s13, s12, 31
	s_add_i32 s21, s21, 0
	s_add_u32 s12, s12, s3
	s_addc_u32 s13, s13, 0
	v_mov_b32_e32 v200, s21
	s_lshl_b64 s[12:13], s[12:13], 11
	ds_read_b32 v225, v200 offset:24576
	v_lshl_add_u64 v[200:201], v[146:147], 0, s[12:13]
	global_load_dwordx4 v[208:211], v[200:201], off offset:16
	global_load_dwordx4 v[212:215], v[200:201], off
	v_readfirstlane_b32 s19, v206
	s_addk_i32 s19, 0x800
	s_lshl_b32 s12, s19, 2
	s_ashr_i32 s13, s19, 31
	s_add_i32 s12, s12, 0
	v_mov_b32_e32 v200, s12
	s_add_u32 s12, s19, s3
	s_addc_u32 s13, s13, 0
	s_lshl_b64 s[12:13], s[12:13], 11
	v_lshl_add_u64 v[204:205], v[146:147], 0, s[12:13]
	ds_read_b32 v224, v200 offset:24576
	global_load_dwordx4 v[200:203], v[204:205], off offset:16
	s_nop 0
	global_load_dwordx4 v[204:207], v[204:205], off
	s_add_i32 s5, s5, 32
	s_or_b32 s12, s28, 0x400
	s_mov_b32 s13, s29
	s_add_i32 s10, s10, 4
	s_waitcnt vmcnt(15)
	v_lshlrev_b32_e32 v180, 16, v126
	s_waitcnt vmcnt(14)
	v_lshlrev_b32_e32 v134, 16, v156
	v_and_b32_e32 v156, 0xffff0000, v156
	v_and_b32_e32 v181, 0xffff0000, v126
	s_waitcnt lgkmcnt(3)
	v_mul_f32_e32 v126, v125, v134
	v_lshlrev_b32_e32 v176, 16, v157
	v_lshlrev_b32_e32 v182, 16, v127
	v_and_b32_e32 v183, 0xffff0000, v127
	v_fma_f32 v127, v82, v126, v78
	v_mul_f32_e32 v126, v125, v156
	v_and_b32_e32 v157, 0xffff0000, v157
	v_lshlrev_b32_e32 v184, 16, v128
	v_and_b32_e32 v185, 0xffff0000, v128
	v_fma_f32 v128, v83, v126, v79
	v_mul_f32_e32 v126, v125, v176
	v_fma_f32 v134, v84, v126, v80
	v_mul_f32_e32 v126, v125, v157
	v_fma_f32 v156, v85, v126, v81
	v_mov_b32_e32 v126, 0
	v_cvt_pk_fp8_f32 v126, v127, v128
	v_lshlrev_b32_e32 v177, 16, v158
	v_and_b32_e32 v158, 0xffff0000, v158
	v_mul_f32_e32 v127, v125, v177
	v_lshlrev_b32_e32 v179, 16, v159
	v_fma_f32 v128, v86, v127, v74
	v_mul_f32_e32 v127, v125, v158
	v_and_b32_e32 v159, 0xffff0000, v159
	v_cvt_pk_fp8_f32 v126, v134, v156 op_sel:[0,0,1]
	v_fma_f32 v134, v87, v127, v75
	v_mul_f32_e32 v127, v125, v179
	v_fma_f32 v156, v88, v127, v76
	v_mul_f32_e32 v127, v125, v159
	v_fma_f32 v157, v89, v127, v77
	v_mov_b32_e32 v127, 0
	v_cvt_pk_fp8_f32 v127, v128, v134
	v_mul_f32_e32 v128, v125, v180
	v_fma_f32 v134, v90, v128, v70
	v_mul_f32_e32 v128, v125, v181
	v_cvt_pk_fp8_f32 v127, v156, v157 op_sel:[0,0,1]
	v_fma_f32 v156, v91, v128, v71
	v_mul_f32_e32 v128, v125, v182
	v_fma_f32 v157, v92, v128, v72
	v_mul_f32_e32 v128, v125, v183
	v_fma_f32 v158, v93, v128, v73
	v_mov_b32_e32 v128, 0
	v_cvt_pk_fp8_f32 v128, v134, v156
	v_lshlrev_b32_e32 v186, 16, v129
	v_and_b32_e32 v129, 0xffff0000, v129
	v_mul_f32_e32 v134, v125, v184
	v_mul_f32_e32 v156, v125, v185
	v_cvt_pk_fp8_f32 v128, v157, v158 op_sel:[0,0,1]
	v_fma_f32 v134, v94, v134, v66
	v_fma_f32 v156, v95, v156, v67
	v_mul_f32_e32 v157, v125, v186
	v_mul_f32_e32 v125, v125, v129
	v_mov_b32_e32 v129, 0
	v_cvt_pk_fp8_f32 v129, v134, v156
	v_fma_f32 v157, v96, v157, v68
	v_fma_f32 v125, v97, v125, v69
	s_waitcnt vmcnt(13)
	v_and_b32_e32 v134, 0xffff0000, v114
	v_cvt_pk_fp8_f32 v129, v157, v125 op_sel:[0,0,1]
	v_lshl_add_u64 v[156:157], v[148:149], 0, s[28:29]
	s_waitcnt vmcnt(12)
	v_lshlrev_b32_e32 v125, 16, v118
	v_and_b32_e32 v118, 0xffff0000, v118
	global_store_dwordx4 v[156:157], v[126:129], off
	v_lshlrev_b32_e32 v156, 16, v115
	v_and_b32_e32 v157, 0xffff0000, v115
	v_lshlrev_b32_e32 v129, 16, v114
	s_waitcnt lgkmcnt(2)
	v_mul_f32_e32 v114, v124, v125
	v_lshlrev_b32_e32 v126, 16, v119
	v_fma_f32 v115, v82, v114, v78
	v_mul_f32_e32 v114, v124, v118
	v_and_b32_e32 v119, 0xffff0000, v119
	v_lshlrev_b32_e32 v158, 16, v116
	v_and_b32_e32 v159, 0xffff0000, v116
	v_fma_f32 v116, v83, v114, v79
	v_mul_f32_e32 v114, v124, v126
	v_fma_f32 v118, v84, v114, v80
	v_mul_f32_e32 v114, v124, v119
	v_fma_f32 v119, v85, v114, v81
	v_mov_b32_e32 v114, 0
	v_cvt_pk_fp8_f32 v114, v115, v116
	v_lshlrev_b32_e32 v127, 16, v120
	v_and_b32_e32 v120, 0xffff0000, v120
	v_mul_f32_e32 v115, v124, v127
	v_lshlrev_b32_e32 v128, 16, v121
	v_fma_f32 v116, v86, v115, v74
	v_mul_f32_e32 v115, v124, v120
	v_and_b32_e32 v121, 0xffff0000, v121
	v_cvt_pk_fp8_f32 v114, v118, v119 op_sel:[0,0,1]
	v_fma_f32 v118, v87, v115, v75
	v_mul_f32_e32 v115, v124, v128
	v_fma_f32 v119, v88, v115, v76
	v_mul_f32_e32 v115, v124, v121
	v_fma_f32 v120, v89, v115, v77
	v_mov_b32_e32 v115, 0
	v_cvt_pk_fp8_f32 v115, v116, v118
	v_mul_f32_e32 v116, v124, v129
	v_fma_f32 v118, v90, v116, v70
	v_mul_f32_e32 v116, v124, v134
	v_cvt_pk_fp8_f32 v115, v119, v120 op_sel:[0,0,1]
	v_fma_f32 v119, v91, v116, v71
	v_mul_f32_e32 v116, v124, v156
	v_fma_f32 v120, v92, v116, v72
	v_mul_f32_e32 v116, v124, v157
	v_fma_f32 v121, v93, v116, v73
	v_mov_b32_e32 v116, 0
	v_cvt_pk_fp8_f32 v116, v118, v119
	v_lshlrev_b32_e32 v176, 16, v117
	v_and_b32_e32 v117, 0xffff0000, v117
	v_mul_f32_e32 v118, v124, v158
	v_mul_f32_e32 v119, v124, v159
	v_mul_f32_e32 v117, v124, v117
	v_cvt_pk_fp8_f32 v116, v120, v121 op_sel:[0,0,1]
	v_fma_f32 v118, v94, v118, v66
	v_fma_f32 v119, v95, v119, v67
	v_fma_f32 v121, v97, v117, v69
	v_mov_b32_e32 v117, 0
	v_cvt_pk_fp8_f32 v117, v118, v119
	v_mul_f32_e32 v120, v124, v176
	v_fma_f32 v120, v96, v120, v68
	v_lshl_add_u64 v[118:119], v[148:149], 0, s[12:13]
	v_cvt_pk_fp8_f32 v117, v120, v121 op_sel:[0,0,1]
	s_waitcnt vmcnt(12)
	v_lshlrev_b32_e32 v120, 16, v107
	v_and_b32_e32 v121, 0xffff0000, v107
	v_lshlrev_b32_e32 v124, 16, v108
	global_store_dwordx4 v[118:119], v[114:117], off
	v_lshlrev_b32_e32 v118, 16, v106
	v_and_b32_e32 v119, 0xffff0000, v106
	s_waitcnt vmcnt(12)
	v_lshlrev_b32_e32 v114, 16, v110
	v_and_b32_e32 v110, 0xffff0000, v110
	s_waitcnt lgkmcnt(1)
	v_mul_f32_e32 v106, v123, v114
	v_lshlrev_b32_e32 v115, 16, v111
	v_fma_f32 v107, v82, v106, v78
	v_mul_f32_e32 v106, v123, v110
	v_and_b32_e32 v111, 0xffff0000, v111
	v_and_b32_e32 v125, 0xffff0000, v108
	v_fma_f32 v108, v83, v106, v79
	v_mul_f32_e32 v106, v123, v115
	v_fma_f32 v110, v84, v106, v80
	v_mul_f32_e32 v106, v123, v111
	v_fma_f32 v111, v85, v106, v81
	v_mov_b32_e32 v106, 0
	v_cvt_pk_fp8_f32 v106, v107, v108
	v_lshlrev_b32_e32 v116, 16, v112
	v_and_b32_e32 v112, 0xffff0000, v112
	v_mul_f32_e32 v107, v123, v116
	v_lshlrev_b32_e32 v117, 16, v113
	v_fma_f32 v108, v86, v107, v74
	v_mul_f32_e32 v107, v123, v112
	v_and_b32_e32 v113, 0xffff0000, v113
	v_cvt_pk_fp8_f32 v106, v110, v111 op_sel:[0,0,1]
	v_fma_f32 v110, v87, v107, v75
	v_mul_f32_e32 v107, v123, v117
	v_fma_f32 v111, v88, v107, v76
	v_mul_f32_e32 v107, v123, v113
	v_fma_f32 v112, v89, v107, v77
	v_mov_b32_e32 v107, 0
	v_cvt_pk_fp8_f32 v107, v108, v110
	v_mul_f32_e32 v108, v123, v118
	v_fma_f32 v110, v90, v108, v70
	v_mul_f32_e32 v108, v123, v119
	v_cvt_pk_fp8_f32 v107, v111, v112 op_sel:[0,0,1]
	v_fma_f32 v111, v91, v108, v71
	v_mul_f32_e32 v108, v123, v120
	v_fma_f32 v112, v92, v108, v72
	v_mul_f32_e32 v108, v123, v121
	v_fma_f32 v113, v93, v108, v73
	v_mov_b32_e32 v108, 0
	v_cvt_pk_fp8_f32 v108, v110, v111
	v_lshlrev_b32_e32 v126, 16, v109
	v_and_b32_e32 v109, 0xffff0000, v109
	v_mul_f32_e32 v110, v123, v124
	v_mul_f32_e32 v111, v123, v125
	v_mul_f32_e32 v109, v123, v109
	v_cvt_pk_fp8_f32 v108, v112, v113 op_sel:[0,0,1]
	v_fma_f32 v110, v94, v110, v66
	v_fma_f32 v111, v95, v111, v67
	v_fma_f32 v113, v97, v109, v69
	v_mov_b32_e32 v109, 0
	v_cvt_pk_fp8_f32 v109, v110, v111
	v_mul_f32_e32 v112, v123, v126
	v_fma_f32 v112, v96, v112, v68
	s_or_b32 s12, s28, 0x800
	v_cvt_pk_fp8_f32 v109, v112, v113 op_sel:[0,0,1]
	v_lshl_add_u64 v[110:111], v[148:149], 0, s[12:13]
	s_waitcnt vmcnt(11)
	v_lshlrev_b32_e32 v112, 16, v99
	v_and_b32_e32 v113, 0xffff0000, v99
	global_store_dwordx4 v[110:111], v[106:109], off
	v_lshlrev_b32_e32 v110, 16, v98
	v_and_b32_e32 v111, 0xffff0000, v98
	s_waitcnt vmcnt(11)
	v_lshlrev_b32_e32 v106, 16, v102
	v_and_b32_e32 v102, 0xffff0000, v102
	s_waitcnt lgkmcnt(0)
	v_mul_f32_e32 v98, v122, v106
	v_lshlrev_b32_e32 v107, 16, v103
	v_fma_f32 v99, v82, v98, v78
	v_mul_f32_e32 v98, v122, v102
	v_and_b32_e32 v103, 0xffff0000, v103
	v_lshlrev_b32_e32 v114, 16, v100
	v_and_b32_e32 v115, 0xffff0000, v100
	v_fma_f32 v100, v83, v98, v79
	v_mul_f32_e32 v98, v122, v107
	v_fma_f32 v102, v84, v98, v80
	v_mul_f32_e32 v98, v122, v103
	v_fma_f32 v103, v85, v98, v81
	v_mov_b32_e32 v98, 0
	v_cvt_pk_fp8_f32 v98, v99, v100
	v_lshlrev_b32_e32 v108, 16, v104
	v_and_b32_e32 v104, 0xffff0000, v104
	v_mul_f32_e32 v99, v122, v108
	v_lshlrev_b32_e32 v109, 16, v105
	v_fma_f32 v100, v86, v99, v74
	v_mul_f32_e32 v99, v122, v104
	v_and_b32_e32 v105, 0xffff0000, v105
	v_cvt_pk_fp8_f32 v98, v102, v103 op_sel:[0,0,1]
	v_fma_f32 v102, v87, v99, v75
	v_mul_f32_e32 v99, v122, v109
	v_fma_f32 v103, v88, v99, v76
	v_mul_f32_e32 v99, v122, v105
	v_fma_f32 v104, v89, v99, v77
	v_mov_b32_e32 v99, 0
	v_cvt_pk_fp8_f32 v99, v100, v102
	v_mul_f32_e32 v100, v122, v110
	v_fma_f32 v102, v90, v100, v70
	v_mul_f32_e32 v100, v122, v111
	v_cvt_pk_fp8_f32 v99, v103, v104 op_sel:[0,0,1]
	v_fma_f32 v103, v91, v100, v71
	v_mul_f32_e32 v100, v122, v112
	v_fma_f32 v104, v92, v100, v72
	v_mul_f32_e32 v100, v122, v113
	v_fma_f32 v105, v93, v100, v73
	v_mov_b32_e32 v100, 0
	v_cvt_pk_fp8_f32 v100, v102, v103
	v_lshlrev_b32_e32 v116, 16, v101
	v_and_b32_e32 v101, 0xffff0000, v101
	v_mul_f32_e32 v102, v122, v114
	v_mul_f32_e32 v103, v122, v115
	v_mul_f32_e32 v101, v122, v101
	v_cvt_pk_fp8_f32 v100, v104, v105 op_sel:[0,0,1]
	v_fma_f32 v102, v94, v102, v66
	v_fma_f32 v103, v95, v103, v67
	v_fma_f32 v105, v97, v101, v69
	v_mov_b32_e32 v101, 0
	v_cvt_pk_fp8_f32 v101, v102, v103
	v_mul_f32_e32 v104, v122, v116
	v_fma_f32 v104, v96, v104, v68
	s_or_b32 s12, s28, 0xc00
	v_cvt_pk_fp8_f32 v101, v104, v105 op_sel:[0,0,1]
	s_add_u32 s28, s28, 0x1000
	s_addc_u32 s29, s29, 0
	v_lshl_add_u64 v[102:103], v[148:149], 0, s[12:13]
	global_store_dwordx4 v[102:103], v[98:101], off
	v_mov_b32_e32 v102, s5
	ds_read_b128 v[98:101], v102
	ds_read_b128 v[102:105], v102 offset:16
	s_waitcnt lgkmcnt(1)
	v_readfirstlane_b32 s12, v98
	s_addk_i32 s12, 0x800
	s_lshl_b32 s21, s12, 2
	s_ashr_i32 s13, s12, 31
	s_add_i32 s21, s21, 0
	s_add_u32 s12, s12, s3
	s_addc_u32 s13, s13, 0
	v_mov_b32_e32 v98, s21
	s_lshl_b64 s[12:13], s[12:13], 11
	ds_read_b32 v125, v98 offset:24576
	v_lshl_add_u64 v[98:99], v[146:147], 0, s[12:13]
	global_load_dwordx4 v[126:129], v[98:99], off offset:16
	global_load_dwordx4 v[156:159], v[98:99], off
	v_readfirstlane_b32 s19, v100
	s_addk_i32 s19, 0x800
	s_lshl_b32 s12, s19, 2
	s_ashr_i32 s13, s19, 31
	s_add_i32 s12, s12, 0
	v_mov_b32_e32 v98, s12
	s_add_u32 s12, s19, s3
	s_addc_u32 s13, s13, 0
	s_lshl_b64 s[12:13], s[12:13], 11
	ds_read_b32 v124, v98 offset:24576
	v_lshl_add_u64 v[98:99], v[146:147], 0, s[12:13]
	global_load_dwordx4 v[114:117], v[98:99], off offset:16
	global_load_dwordx4 v[118:121], v[98:99], off
	s_waitcnt lgkmcnt(2)
	v_readfirstlane_b32 s12, v102
	s_addk_i32 s12, 0x800
	s_lshl_b32 s21, s12, 2
	s_ashr_i32 s13, s12, 31
	s_add_i32 s21, s21, 0
	s_add_u32 s12, s12, s3
	s_addc_u32 s13, s13, 0
	v_mov_b32_e32 v98, s21
	s_lshl_b64 s[12:13], s[12:13], 11
	ds_read_b32 v123, v98 offset:24576
	v_lshl_add_u64 v[98:99], v[146:147], 0, s[12:13]
	global_load_dwordx4 v[106:109], v[98:99], off offset:16
	global_load_dwordx4 v[110:113], v[98:99], off
	v_readfirstlane_b32 s19, v104
	s_addk_i32 s19, 0x800
	s_lshl_b32 s12, s19, 2
	s_ashr_i32 s13, s19, 31
	s_add_i32 s12, s12, 0
	v_mov_b32_e32 v98, s12
	s_add_u32 s12, s19, s3
	s_addc_u32 s13, s13, 0
	s_lshl_b64 s[12:13], s[12:13], 11
	v_lshl_add_u64 v[102:103], v[146:147], 0, s[12:13]
	ds_read_b32 v122, v98 offset:24576
	global_load_dwordx4 v[98:101], v[102:103], off offset:16
	s_nop 0
	global_load_dwordx4 v[102:105], v[102:103], off
	s_add_i32 s5, s5, 32
	s_or_b32 s12, s28, 0x400
	s_mov_b32 s13, s29
	s_add_i32 s10, s10, 4
	s_waitcnt vmcnt(19)
	v_lshlrev_b32_e32 v180, 16, v228
	s_waitcnt vmcnt(18)
	v_lshlrev_b32_e32 v134, 16, v232
	v_and_b32_e32 v232, 0xffff0000, v232
	v_and_b32_e32 v181, 0xffff0000, v228
	s_waitcnt lgkmcnt(3)
	v_mul_f32_e32 v228, v227, v134
	v_lshlrev_b32_e32 v176, 16, v233
	v_lshlrev_b32_e32 v182, 16, v229
	v_and_b32_e32 v183, 0xffff0000, v229
	v_fma_f32 v229, v82, v228, v78
	v_mul_f32_e32 v228, v227, v232
	v_and_b32_e32 v233, 0xffff0000, v233
	v_lshlrev_b32_e32 v184, 16, v230
	v_and_b32_e32 v185, 0xffff0000, v230
	v_fma_f32 v230, v83, v228, v79
	v_mul_f32_e32 v228, v227, v176
	v_fma_f32 v134, v84, v228, v80
	v_mul_f32_e32 v228, v227, v233
	v_fma_f32 v232, v85, v228, v81
	v_mov_b32_e32 v228, 0
	v_cvt_pk_fp8_f32 v228, v229, v230
	v_lshlrev_b32_e32 v177, 16, v234
	v_and_b32_e32 v234, 0xffff0000, v234
	v_mul_f32_e32 v229, v227, v177
	v_lshlrev_b32_e32 v179, 16, v235
	v_fma_f32 v230, v86, v229, v74
	v_mul_f32_e32 v229, v227, v234
	v_and_b32_e32 v235, 0xffff0000, v235
	v_cvt_pk_fp8_f32 v228, v134, v232 op_sel:[0,0,1]
	v_fma_f32 v134, v87, v229, v75
	v_mul_f32_e32 v229, v227, v179
	v_fma_f32 v232, v88, v229, v76
	v_mul_f32_e32 v229, v227, v235
	v_fma_f32 v233, v89, v229, v77
	v_mov_b32_e32 v229, 0
	v_cvt_pk_fp8_f32 v229, v230, v134
	v_mul_f32_e32 v230, v227, v180
	v_fma_f32 v134, v90, v230, v70
	v_mul_f32_e32 v230, v227, v181
	v_cvt_pk_fp8_f32 v229, v232, v233 op_sel:[0,0,1]
	v_fma_f32 v232, v91, v230, v71
	v_mul_f32_e32 v230, v227, v182
	v_fma_f32 v233, v92, v230, v72
	v_mul_f32_e32 v230, v227, v183
	v_fma_f32 v234, v93, v230, v73
	v_mov_b32_e32 v230, 0
	v_cvt_pk_fp8_f32 v230, v134, v232
	v_lshlrev_b32_e32 v186, 16, v231
	v_and_b32_e32 v231, 0xffff0000, v231
	v_mul_f32_e32 v134, v227, v184
	v_mul_f32_e32 v232, v227, v185
	v_cvt_pk_fp8_f32 v230, v233, v234 op_sel:[0,0,1]
	v_fma_f32 v134, v94, v134, v66
	v_fma_f32 v232, v95, v232, v67
	v_mul_f32_e32 v233, v227, v186
	v_mul_f32_e32 v227, v227, v231
	v_mov_b32_e32 v231, 0
	v_cvt_pk_fp8_f32 v231, v134, v232
	v_fma_f32 v233, v96, v233, v68
	v_fma_f32 v227, v97, v227, v69
	s_waitcnt vmcnt(17)
	v_and_b32_e32 v134, 0xffff0000, v216
	v_cvt_pk_fp8_f32 v231, v233, v227 op_sel:[0,0,1]
	v_lshl_add_u64 v[232:233], v[148:149], 0, s[28:29]
	s_waitcnt vmcnt(16)
	v_lshlrev_b32_e32 v227, 16, v220
	v_and_b32_e32 v220, 0xffff0000, v220
	global_store_dwordx4 v[232:233], v[228:231], off
	v_lshlrev_b32_e32 v232, 16, v217
	v_and_b32_e32 v233, 0xffff0000, v217
	v_lshlrev_b32_e32 v231, 16, v216
	s_waitcnt lgkmcnt(2)
	v_mul_f32_e32 v216, v226, v227
	v_lshlrev_b32_e32 v228, 16, v221
	v_fma_f32 v217, v82, v216, v78
	v_mul_f32_e32 v216, v226, v220
	v_and_b32_e32 v221, 0xffff0000, v221
	v_lshlrev_b32_e32 v234, 16, v218
	v_and_b32_e32 v235, 0xffff0000, v218
	v_fma_f32 v218, v83, v216, v79
	v_mul_f32_e32 v216, v226, v228
	v_fma_f32 v220, v84, v216, v80
	v_mul_f32_e32 v216, v226, v221
	v_fma_f32 v221, v85, v216, v81
	v_mov_b32_e32 v216, 0
	v_cvt_pk_fp8_f32 v216, v217, v218
	v_lshlrev_b32_e32 v229, 16, v222
	v_and_b32_e32 v222, 0xffff0000, v222
	v_mul_f32_e32 v217, v226, v229
	v_lshlrev_b32_e32 v230, 16, v223
	v_fma_f32 v218, v86, v217, v74
	v_mul_f32_e32 v217, v226, v222
	v_and_b32_e32 v223, 0xffff0000, v223
	v_cvt_pk_fp8_f32 v216, v220, v221 op_sel:[0,0,1]
	v_fma_f32 v220, v87, v217, v75
	v_mul_f32_e32 v217, v226, v230
	v_fma_f32 v221, v88, v217, v76
	v_mul_f32_e32 v217, v226, v223
	v_fma_f32 v222, v89, v217, v77
	v_mov_b32_e32 v217, 0
	v_cvt_pk_fp8_f32 v217, v218, v220
	v_mul_f32_e32 v218, v226, v231
	v_fma_f32 v220, v90, v218, v70
	v_mul_f32_e32 v218, v226, v134
	v_cvt_pk_fp8_f32 v217, v221, v222 op_sel:[0,0,1]
	v_fma_f32 v221, v91, v218, v71
	v_mul_f32_e32 v218, v226, v232
	v_fma_f32 v222, v92, v218, v72
	v_mul_f32_e32 v218, v226, v233
	v_fma_f32 v223, v93, v218, v73
	v_mov_b32_e32 v218, 0
	v_cvt_pk_fp8_f32 v218, v220, v221
	v_lshlrev_b32_e32 v176, 16, v219
	v_and_b32_e32 v219, 0xffff0000, v219
	v_mul_f32_e32 v220, v226, v234
	v_mul_f32_e32 v221, v226, v235
	v_mul_f32_e32 v219, v226, v219
	v_cvt_pk_fp8_f32 v218, v222, v223 op_sel:[0,0,1]
	v_fma_f32 v220, v94, v220, v66
	v_fma_f32 v221, v95, v221, v67
	v_fma_f32 v223, v97, v219, v69
	v_mov_b32_e32 v219, 0
	v_cvt_pk_fp8_f32 v219, v220, v221
	v_mul_f32_e32 v222, v226, v176
	v_fma_f32 v222, v96, v222, v68
	v_lshl_add_u64 v[220:221], v[148:149], 0, s[12:13]
	v_cvt_pk_fp8_f32 v219, v222, v223 op_sel:[0,0,1]
	s_waitcnt vmcnt(16)
	v_lshlrev_b32_e32 v222, 16, v209
	v_and_b32_e32 v223, 0xffff0000, v209
	v_lshlrev_b32_e32 v226, 16, v210
	global_store_dwordx4 v[220:221], v[216:219], off
	v_lshlrev_b32_e32 v220, 16, v208
	v_and_b32_e32 v221, 0xffff0000, v208
	s_waitcnt vmcnt(16)
	v_lshlrev_b32_e32 v216, 16, v212
	v_and_b32_e32 v212, 0xffff0000, v212
	s_waitcnt lgkmcnt(1)
	v_mul_f32_e32 v208, v225, v216
	v_lshlrev_b32_e32 v217, 16, v213
	v_fma_f32 v209, v82, v208, v78
	v_mul_f32_e32 v208, v225, v212
	v_and_b32_e32 v213, 0xffff0000, v213
	v_and_b32_e32 v227, 0xffff0000, v210
	v_fma_f32 v210, v83, v208, v79
	v_mul_f32_e32 v208, v225, v217
	v_fma_f32 v212, v84, v208, v80
	v_mul_f32_e32 v208, v225, v213
	v_fma_f32 v213, v85, v208, v81
	v_mov_b32_e32 v208, 0
	v_cvt_pk_fp8_f32 v208, v209, v210
	v_lshlrev_b32_e32 v218, 16, v214
	v_and_b32_e32 v214, 0xffff0000, v214
	v_mul_f32_e32 v209, v225, v218
	v_lshlrev_b32_e32 v219, 16, v215
	v_fma_f32 v210, v86, v209, v74
	v_mul_f32_e32 v209, v225, v214
	v_and_b32_e32 v215, 0xffff0000, v215
	v_cvt_pk_fp8_f32 v208, v212, v213 op_sel:[0,0,1]
	v_fma_f32 v212, v87, v209, v75
	v_mul_f32_e32 v209, v225, v219
	v_fma_f32 v213, v88, v209, v76
	v_mul_f32_e32 v209, v225, v215
	v_fma_f32 v214, v89, v209, v77
	v_mov_b32_e32 v209, 0
	v_cvt_pk_fp8_f32 v209, v210, v212
	v_mul_f32_e32 v210, v225, v220
	v_fma_f32 v212, v90, v210, v70
	v_mul_f32_e32 v210, v225, v221
	v_cvt_pk_fp8_f32 v209, v213, v214 op_sel:[0,0,1]
	v_fma_f32 v213, v91, v210, v71
	v_mul_f32_e32 v210, v225, v222
	v_fma_f32 v214, v92, v210, v72
	v_mul_f32_e32 v210, v225, v223
	v_fma_f32 v215, v93, v210, v73
	v_mov_b32_e32 v210, 0
	v_cvt_pk_fp8_f32 v210, v212, v213
	v_lshlrev_b32_e32 v228, 16, v211
	v_and_b32_e32 v211, 0xffff0000, v211
	v_mul_f32_e32 v212, v225, v226
	v_mul_f32_e32 v213, v225, v227
	v_mul_f32_e32 v211, v225, v211
	v_cvt_pk_fp8_f32 v210, v214, v215 op_sel:[0,0,1]
	v_fma_f32 v212, v94, v212, v66
	v_fma_f32 v213, v95, v213, v67
	v_fma_f32 v215, v97, v211, v69
	v_mov_b32_e32 v211, 0
	v_cvt_pk_fp8_f32 v211, v212, v213
	v_mul_f32_e32 v214, v225, v228
	v_fma_f32 v214, v96, v214, v68
	s_or_b32 s12, s28, 0x800
	v_cvt_pk_fp8_f32 v211, v214, v215 op_sel:[0,0,1]
	v_lshl_add_u64 v[212:213], v[148:149], 0, s[12:13]
	s_waitcnt vmcnt(15)
	v_lshlrev_b32_e32 v214, 16, v201
	v_and_b32_e32 v215, 0xffff0000, v201
	global_store_dwordx4 v[212:213], v[208:211], off
	v_lshlrev_b32_e32 v212, 16, v200
	v_and_b32_e32 v213, 0xffff0000, v200
	s_waitcnt vmcnt(15)
	v_lshlrev_b32_e32 v208, 16, v204
	v_and_b32_e32 v204, 0xffff0000, v204
	s_waitcnt lgkmcnt(0)
	v_mul_f32_e32 v200, v224, v208
	v_lshlrev_b32_e32 v209, 16, v205
	v_fma_f32 v201, v82, v200, v78
	v_mul_f32_e32 v200, v224, v204
	v_and_b32_e32 v205, 0xffff0000, v205
	v_lshlrev_b32_e32 v216, 16, v202
	v_and_b32_e32 v217, 0xffff0000, v202
	v_fma_f32 v202, v83, v200, v79
	v_mul_f32_e32 v200, v224, v209
	v_fma_f32 v204, v84, v200, v80
	v_mul_f32_e32 v200, v224, v205
	v_fma_f32 v205, v85, v200, v81
	v_mov_b32_e32 v200, 0
	v_cvt_pk_fp8_f32 v200, v201, v202
	v_lshlrev_b32_e32 v210, 16, v206
	v_and_b32_e32 v206, 0xffff0000, v206
	v_mul_f32_e32 v201, v224, v210
	v_lshlrev_b32_e32 v211, 16, v207
	v_fma_f32 v202, v86, v201, v74
	v_mul_f32_e32 v201, v224, v206
	v_and_b32_e32 v207, 0xffff0000, v207
	v_cvt_pk_fp8_f32 v200, v204, v205 op_sel:[0,0,1]
	v_fma_f32 v204, v87, v201, v75
	v_mul_f32_e32 v201, v224, v211
	v_fma_f32 v205, v88, v201, v76
	v_mul_f32_e32 v201, v224, v207
	v_fma_f32 v206, v89, v201, v77
	v_mov_b32_e32 v201, 0
	v_cvt_pk_fp8_f32 v201, v202, v204
	v_mul_f32_e32 v202, v224, v212
	v_fma_f32 v204, v90, v202, v70
	v_mul_f32_e32 v202, v224, v213
	v_cvt_pk_fp8_f32 v201, v205, v206 op_sel:[0,0,1]
	v_fma_f32 v205, v91, v202, v71
	v_mul_f32_e32 v202, v224, v214
	v_fma_f32 v206, v92, v202, v72
	v_mul_f32_e32 v202, v224, v215
	v_fma_f32 v207, v93, v202, v73
	v_mov_b32_e32 v202, 0
	v_cvt_pk_fp8_f32 v202, v204, v205
	v_lshlrev_b32_e32 v218, 16, v203
	v_and_b32_e32 v203, 0xffff0000, v203
	v_mul_f32_e32 v204, v224, v216
	v_mul_f32_e32 v205, v224, v217
	v_mul_f32_e32 v203, v224, v203
	v_cvt_pk_fp8_f32 v202, v206, v207 op_sel:[0,0,1]
	v_fma_f32 v204, v94, v204, v66
	v_fma_f32 v205, v95, v205, v67
	v_fma_f32 v207, v97, v203, v69
	v_mov_b32_e32 v203, 0
	v_cvt_pk_fp8_f32 v203, v204, v205
	v_mul_f32_e32 v206, v224, v218
	v_fma_f32 v206, v96, v206, v68
	s_or_b32 s12, s28, 0xc00
	v_cvt_pk_fp8_f32 v203, v206, v207 op_sel:[0,0,1]
	s_add_u32 s28, s28, 0x1000
	s_addc_u32 s29, s29, 0
	v_lshl_add_u64 v[204:205], v[148:149], 0, s[12:13]
	global_store_dwordx4 v[204:205], v[200:203], off
	v_mov_b32_e32 v204, s5
	ds_read_b128 v[200:203], v204
	ds_read_b128 v[204:207], v204 offset:16
	s_waitcnt lgkmcnt(1)
	v_readfirstlane_b32 s12, v200
	s_addk_i32 s12, 0x800
	s_lshl_b32 s21, s12, 2
	s_ashr_i32 s13, s12, 31
	s_add_i32 s21, s21, 0
	s_add_u32 s12, s12, s3
	s_addc_u32 s13, s13, 0
	v_mov_b32_e32 v200, s21
	s_lshl_b64 s[12:13], s[12:13], 11
	ds_read_b32 v227, v200 offset:24576
	v_lshl_add_u64 v[200:201], v[146:147], 0, s[12:13]
	global_load_dwordx4 v[228:231], v[200:201], off offset:16
	global_load_dwordx4 v[232:235], v[200:201], off
	v_readfirstlane_b32 s19, v202
	s_addk_i32 s19, 0x800
	s_lshl_b32 s12, s19, 2
	s_ashr_i32 s13, s19, 31
	s_add_i32 s12, s12, 0
	v_mov_b32_e32 v200, s12
	s_add_u32 s12, s19, s3
	s_addc_u32 s13, s13, 0
	s_lshl_b64 s[12:13], s[12:13], 11
	ds_read_b32 v226, v200 offset:24576
	v_lshl_add_u64 v[200:201], v[146:147], 0, s[12:13]
	global_load_dwordx4 v[216:219], v[200:201], off offset:16
	global_load_dwordx4 v[220:223], v[200:201], off
	s_waitcnt lgkmcnt(2)
	v_readfirstlane_b32 s12, v204
	s_addk_i32 s12, 0x800
	s_lshl_b32 s21, s12, 2
	s_ashr_i32 s13, s12, 31
	s_add_i32 s21, s21, 0
	s_add_u32 s12, s12, s3
	s_addc_u32 s13, s13, 0
	v_mov_b32_e32 v200, s21
	s_lshl_b64 s[12:13], s[12:13], 11
	ds_read_b32 v225, v200 offset:24576
	v_lshl_add_u64 v[200:201], v[146:147], 0, s[12:13]
	global_load_dwordx4 v[208:211], v[200:201], off offset:16
	global_load_dwordx4 v[212:215], v[200:201], off
	v_readfirstlane_b32 s19, v206
	s_addk_i32 s19, 0x800
	s_lshl_b32 s12, s19, 2
	s_ashr_i32 s13, s19, 31
	s_add_i32 s12, s12, 0
	v_mov_b32_e32 v200, s12
	s_add_u32 s12, s19, s3
	s_addc_u32 s13, s13, 0
	s_lshl_b64 s[12:13], s[12:13], 11
	v_lshl_add_u64 v[204:205], v[146:147], 0, s[12:13]
	ds_read_b32 v224, v200 offset:24576
	global_load_dwordx4 v[200:203], v[204:205], off offset:16
	s_nop 0
	global_load_dwordx4 v[204:207], v[204:205], off
	s_add_i32 s5, s5, 32
	s_or_b32 s12, s28, 0x400
	s_mov_b32 s13, s29
	s_add_i32 s10, s10, 4
	s_waitcnt vmcnt(19)
	v_lshlrev_b32_e32 v180, 16, v126
	s_waitcnt vmcnt(18)
	v_lshlrev_b32_e32 v134, 16, v156
	v_and_b32_e32 v156, 0xffff0000, v156
	v_and_b32_e32 v181, 0xffff0000, v126
	s_waitcnt lgkmcnt(3)
	v_mul_f32_e32 v126, v125, v134
	v_lshlrev_b32_e32 v176, 16, v157
	v_lshlrev_b32_e32 v182, 16, v127
	v_and_b32_e32 v183, 0xffff0000, v127
	v_fma_f32 v127, v82, v126, v78
	v_mul_f32_e32 v126, v125, v156
	v_and_b32_e32 v157, 0xffff0000, v157
	v_lshlrev_b32_e32 v184, 16, v128
	v_and_b32_e32 v185, 0xffff0000, v128
	v_fma_f32 v128, v83, v126, v79
	v_mul_f32_e32 v126, v125, v176
	v_fma_f32 v134, v84, v126, v80
	v_mul_f32_e32 v126, v125, v157
	v_fma_f32 v156, v85, v126, v81
	v_mov_b32_e32 v126, 0
	v_cvt_pk_fp8_f32 v126, v127, v128
	v_lshlrev_b32_e32 v177, 16, v158
	v_and_b32_e32 v158, 0xffff0000, v158
	v_mul_f32_e32 v127, v125, v177
	v_lshlrev_b32_e32 v179, 16, v159
	v_fma_f32 v128, v86, v127, v74
	v_mul_f32_e32 v127, v125, v158
	v_and_b32_e32 v159, 0xffff0000, v159
	v_cvt_pk_fp8_f32 v126, v134, v156 op_sel:[0,0,1]
	v_fma_f32 v134, v87, v127, v75
	v_mul_f32_e32 v127, v125, v179
	v_fma_f32 v156, v88, v127, v76
	v_mul_f32_e32 v127, v125, v159
	v_fma_f32 v157, v89, v127, v77
	v_mov_b32_e32 v127, 0
	v_cvt_pk_fp8_f32 v127, v128, v134
	v_mul_f32_e32 v128, v125, v180
	v_fma_f32 v134, v90, v128, v70
	v_mul_f32_e32 v128, v125, v181
	v_cvt_pk_fp8_f32 v127, v156, v157 op_sel:[0,0,1]
	v_fma_f32 v156, v91, v128, v71
	v_mul_f32_e32 v128, v125, v182
	v_fma_f32 v157, v92, v128, v72
	v_mul_f32_e32 v128, v125, v183
	v_fma_f32 v158, v93, v128, v73
	v_mov_b32_e32 v128, 0
	v_cvt_pk_fp8_f32 v128, v134, v156
	v_lshlrev_b32_e32 v186, 16, v129
	v_and_b32_e32 v129, 0xffff0000, v129
	v_mul_f32_e32 v134, v125, v184
	v_mul_f32_e32 v156, v125, v185
	v_cvt_pk_fp8_f32 v128, v157, v158 op_sel:[0,0,1]
	v_fma_f32 v134, v94, v134, v66
	v_fma_f32 v156, v95, v156, v67
	v_mul_f32_e32 v157, v125, v186
	v_mul_f32_e32 v125, v125, v129
	v_mov_b32_e32 v129, 0
	v_cvt_pk_fp8_f32 v129, v134, v156
	v_fma_f32 v157, v96, v157, v68
	v_fma_f32 v125, v97, v125, v69
	s_waitcnt vmcnt(17)
	v_and_b32_e32 v134, 0xffff0000, v114
	v_cvt_pk_fp8_f32 v129, v157, v125 op_sel:[0,0,1]
	v_lshl_add_u64 v[156:157], v[148:149], 0, s[28:29]
	s_waitcnt vmcnt(16)
	v_lshlrev_b32_e32 v125, 16, v118
	v_and_b32_e32 v118, 0xffff0000, v118
	global_store_dwordx4 v[156:157], v[126:129], off
	v_lshlrev_b32_e32 v156, 16, v115
	v_and_b32_e32 v157, 0xffff0000, v115
	v_lshlrev_b32_e32 v129, 16, v114
	s_waitcnt lgkmcnt(2)
	v_mul_f32_e32 v114, v124, v125
	v_lshlrev_b32_e32 v126, 16, v119
	v_fma_f32 v115, v82, v114, v78
	v_mul_f32_e32 v114, v124, v118
	v_and_b32_e32 v119, 0xffff0000, v119
	v_lshlrev_b32_e32 v158, 16, v116
	v_and_b32_e32 v159, 0xffff0000, v116
	v_fma_f32 v116, v83, v114, v79
	v_mul_f32_e32 v114, v124, v126
	v_fma_f32 v118, v84, v114, v80
	v_mul_f32_e32 v114, v124, v119
	v_fma_f32 v119, v85, v114, v81
	v_mov_b32_e32 v114, 0
	v_cvt_pk_fp8_f32 v114, v115, v116
	v_lshlrev_b32_e32 v127, 16, v120
	v_and_b32_e32 v120, 0xffff0000, v120
	v_mul_f32_e32 v115, v124, v127
	v_lshlrev_b32_e32 v128, 16, v121
	v_fma_f32 v116, v86, v115, v74
	v_mul_f32_e32 v115, v124, v120
	v_and_b32_e32 v121, 0xffff0000, v121
	v_cvt_pk_fp8_f32 v114, v118, v119 op_sel:[0,0,1]
	v_fma_f32 v118, v87, v115, v75
	v_mul_f32_e32 v115, v124, v128
	v_fma_f32 v119, v88, v115, v76
	v_mul_f32_e32 v115, v124, v121
	v_fma_f32 v120, v89, v115, v77
	v_mov_b32_e32 v115, 0
	v_cvt_pk_fp8_f32 v115, v116, v118
	v_mul_f32_e32 v116, v124, v129
	v_fma_f32 v118, v90, v116, v70
	v_mul_f32_e32 v116, v124, v134
	v_cvt_pk_fp8_f32 v115, v119, v120 op_sel:[0,0,1]
	v_fma_f32 v119, v91, v116, v71
	v_mul_f32_e32 v116, v124, v156
	v_fma_f32 v120, v92, v116, v72
	v_mul_f32_e32 v116, v124, v157
	v_fma_f32 v121, v93, v116, v73
	v_mov_b32_e32 v116, 0
	v_cvt_pk_fp8_f32 v116, v118, v119
	v_lshlrev_b32_e32 v176, 16, v117
	v_and_b32_e32 v117, 0xffff0000, v117
	v_mul_f32_e32 v118, v124, v158
	v_mul_f32_e32 v119, v124, v159
	v_mul_f32_e32 v117, v124, v117
	v_cvt_pk_fp8_f32 v116, v120, v121 op_sel:[0,0,1]
	v_fma_f32 v118, v94, v118, v66
	v_fma_f32 v119, v95, v119, v67
	v_fma_f32 v121, v97, v117, v69
	v_mov_b32_e32 v117, 0
	v_cvt_pk_fp8_f32 v117, v118, v119
	v_mul_f32_e32 v120, v124, v176
	v_fma_f32 v120, v96, v120, v68
	v_lshl_add_u64 v[118:119], v[148:149], 0, s[12:13]
	v_cvt_pk_fp8_f32 v117, v120, v121 op_sel:[0,0,1]
	s_waitcnt vmcnt(16)
	v_lshlrev_b32_e32 v120, 16, v107
	v_and_b32_e32 v121, 0xffff0000, v107
	v_lshlrev_b32_e32 v124, 16, v108
	global_store_dwordx4 v[118:119], v[114:117], off
	v_lshlrev_b32_e32 v118, 16, v106
	v_and_b32_e32 v119, 0xffff0000, v106
	s_waitcnt vmcnt(16)
	v_lshlrev_b32_e32 v114, 16, v110
	v_and_b32_e32 v110, 0xffff0000, v110
	s_waitcnt lgkmcnt(1)
	v_mul_f32_e32 v106, v123, v114
	v_lshlrev_b32_e32 v115, 16, v111
	v_fma_f32 v107, v82, v106, v78
	v_mul_f32_e32 v106, v123, v110
	v_and_b32_e32 v111, 0xffff0000, v111
	v_and_b32_e32 v125, 0xffff0000, v108
	v_fma_f32 v108, v83, v106, v79
	v_mul_f32_e32 v106, v123, v115
	v_fma_f32 v110, v84, v106, v80
	v_mul_f32_e32 v106, v123, v111
	v_fma_f32 v111, v85, v106, v81
	v_mov_b32_e32 v106, 0
	v_cvt_pk_fp8_f32 v106, v107, v108
	v_lshlrev_b32_e32 v116, 16, v112
	v_and_b32_e32 v112, 0xffff0000, v112
	v_mul_f32_e32 v107, v123, v116
	v_lshlrev_b32_e32 v117, 16, v113
	v_fma_f32 v108, v86, v107, v74
	v_mul_f32_e32 v107, v123, v112
	v_and_b32_e32 v113, 0xffff0000, v113
	v_cvt_pk_fp8_f32 v106, v110, v111 op_sel:[0,0,1]
	v_fma_f32 v110, v87, v107, v75
	v_mul_f32_e32 v107, v123, v117
	v_fma_f32 v111, v88, v107, v76
	v_mul_f32_e32 v107, v123, v113
	v_fma_f32 v112, v89, v107, v77
	v_mov_b32_e32 v107, 0
	v_cvt_pk_fp8_f32 v107, v108, v110
	v_mul_f32_e32 v108, v123, v118
	v_fma_f32 v110, v90, v108, v70
	v_mul_f32_e32 v108, v123, v119
	v_cvt_pk_fp8_f32 v107, v111, v112 op_sel:[0,0,1]
	v_fma_f32 v111, v91, v108, v71
	v_mul_f32_e32 v108, v123, v120
	v_fma_f32 v112, v92, v108, v72
	v_mul_f32_e32 v108, v123, v121
	v_fma_f32 v113, v93, v108, v73
	v_mov_b32_e32 v108, 0
	v_cvt_pk_fp8_f32 v108, v110, v111
	v_lshlrev_b32_e32 v126, 16, v109
	v_and_b32_e32 v109, 0xffff0000, v109
	v_mul_f32_e32 v110, v123, v124
	v_mul_f32_e32 v111, v123, v125
	v_mul_f32_e32 v109, v123, v109
	v_cvt_pk_fp8_f32 v108, v112, v113 op_sel:[0,0,1]
	v_fma_f32 v110, v94, v110, v66
	v_fma_f32 v111, v95, v111, v67
	v_fma_f32 v113, v97, v109, v69
	v_mov_b32_e32 v109, 0
	v_cvt_pk_fp8_f32 v109, v110, v111
	v_mul_f32_e32 v112, v123, v126
	v_fma_f32 v112, v96, v112, v68
	s_or_b32 s12, s28, 0x800
	v_cvt_pk_fp8_f32 v109, v112, v113 op_sel:[0,0,1]
	v_lshl_add_u64 v[110:111], v[148:149], 0, s[12:13]
	s_waitcnt vmcnt(15)
	v_lshlrev_b32_e32 v112, 16, v99
	v_and_b32_e32 v113, 0xffff0000, v99
	global_store_dwordx4 v[110:111], v[106:109], off
	v_lshlrev_b32_e32 v110, 16, v98
	v_and_b32_e32 v111, 0xffff0000, v98
	s_waitcnt vmcnt(15)
	v_lshlrev_b32_e32 v106, 16, v102
	v_and_b32_e32 v102, 0xffff0000, v102
	s_waitcnt lgkmcnt(0)
	v_mul_f32_e32 v98, v122, v106
	v_lshlrev_b32_e32 v107, 16, v103
	v_fma_f32 v99, v82, v98, v78
	v_mul_f32_e32 v98, v122, v102
	v_and_b32_e32 v103, 0xffff0000, v103
	v_lshlrev_b32_e32 v114, 16, v100
	v_and_b32_e32 v115, 0xffff0000, v100
	v_fma_f32 v100, v83, v98, v79
	v_mul_f32_e32 v98, v122, v107
	v_fma_f32 v102, v84, v98, v80
	v_mul_f32_e32 v98, v122, v103
	v_fma_f32 v103, v85, v98, v81
	v_mov_b32_e32 v98, 0
	v_cvt_pk_fp8_f32 v98, v99, v100
	v_lshlrev_b32_e32 v108, 16, v104
	v_and_b32_e32 v104, 0xffff0000, v104
	v_mul_f32_e32 v99, v122, v108
	v_lshlrev_b32_e32 v109, 16, v105
	v_fma_f32 v100, v86, v99, v74
	v_mul_f32_e32 v99, v122, v104
	v_and_b32_e32 v105, 0xffff0000, v105
	v_cvt_pk_fp8_f32 v98, v102, v103 op_sel:[0,0,1]
	v_fma_f32 v102, v87, v99, v75
	v_mul_f32_e32 v99, v122, v109
	v_fma_f32 v103, v88, v99, v76
	v_mul_f32_e32 v99, v122, v105
	v_fma_f32 v104, v89, v99, v77
	v_mov_b32_e32 v99, 0
	v_cvt_pk_fp8_f32 v99, v100, v102
	v_mul_f32_e32 v100, v122, v110
	v_fma_f32 v102, v90, v100, v70
	v_mul_f32_e32 v100, v122, v111
	v_cvt_pk_fp8_f32 v99, v103, v104 op_sel:[0,0,1]
	v_fma_f32 v103, v91, v100, v71
	v_mul_f32_e32 v100, v122, v112
	v_fma_f32 v104, v92, v100, v72
	v_mul_f32_e32 v100, v122, v113
	v_fma_f32 v105, v93, v100, v73
	v_mov_b32_e32 v100, 0
	v_cvt_pk_fp8_f32 v100, v102, v103
	v_lshlrev_b32_e32 v116, 16, v101
	v_and_b32_e32 v101, 0xffff0000, v101
	v_mul_f32_e32 v102, v122, v114
	v_mul_f32_e32 v103, v122, v115
	v_mul_f32_e32 v101, v122, v101
	v_cvt_pk_fp8_f32 v100, v104, v105 op_sel:[0,0,1]
	v_fma_f32 v102, v94, v102, v66
	v_fma_f32 v103, v95, v103, v67
	v_fma_f32 v105, v97, v101, v69
	v_mov_b32_e32 v101, 0
	v_cvt_pk_fp8_f32 v101, v102, v103
	v_mul_f32_e32 v104, v122, v116
	v_fma_f32 v104, v96, v104, v68
	s_or_b32 s12, s28, 0xc00
	v_cvt_pk_fp8_f32 v101, v104, v105 op_sel:[0,0,1]
	s_add_u32 s28, s28, 0x1000
	s_addc_u32 s29, s29, 0
	v_lshl_add_u64 v[102:103], v[148:149], 0, s[12:13]
	global_store_dwordx4 v[102:103], v[98:101], off
	s_or_b32 s12, s28, 0x400
	s_mov_b32 s13, s29
	s_add_i32 s10, s10, 4
	s_waitcnt vmcnt(11)
	v_lshlrev_b32_e32 v180, 16, v228
	s_waitcnt vmcnt(10)
	v_lshlrev_b32_e32 v134, 16, v232
	v_and_b32_e32 v232, 0xffff0000, v232
	v_and_b32_e32 v181, 0xffff0000, v228
	s_waitcnt lgkmcnt(3)
	v_mul_f32_e32 v228, v227, v134
	v_lshlrev_b32_e32 v176, 16, v233
	v_lshlrev_b32_e32 v182, 16, v229
	v_and_b32_e32 v183, 0xffff0000, v229
	v_fma_f32 v229, v82, v228, v78
	v_mul_f32_e32 v228, v227, v232
	v_and_b32_e32 v233, 0xffff0000, v233
	v_lshlrev_b32_e32 v184, 16, v230
	v_and_b32_e32 v185, 0xffff0000, v230
	v_fma_f32 v230, v83, v228, v79
	v_mul_f32_e32 v228, v227, v176
	v_fma_f32 v134, v84, v228, v80
	v_mul_f32_e32 v228, v227, v233
	v_fma_f32 v232, v85, v228, v81
	v_mov_b32_e32 v228, 0
	v_cvt_pk_fp8_f32 v228, v229, v230
	v_lshlrev_b32_e32 v177, 16, v234
	v_and_b32_e32 v234, 0xffff0000, v234
	v_mul_f32_e32 v229, v227, v177
	v_lshlrev_b32_e32 v179, 16, v235
	v_fma_f32 v230, v86, v229, v74
	v_mul_f32_e32 v229, v227, v234
	v_and_b32_e32 v235, 0xffff0000, v235
	v_cvt_pk_fp8_f32 v228, v134, v232 op_sel:[0,0,1]
	v_fma_f32 v134, v87, v229, v75
	v_mul_f32_e32 v229, v227, v179
	v_fma_f32 v232, v88, v229, v76
	v_mul_f32_e32 v229, v227, v235
	v_fma_f32 v233, v89, v229, v77
	v_mov_b32_e32 v229, 0
	v_cvt_pk_fp8_f32 v229, v230, v134
	v_mul_f32_e32 v230, v227, v180
	v_fma_f32 v134, v90, v230, v70
	v_mul_f32_e32 v230, v227, v181
	v_cvt_pk_fp8_f32 v229, v232, v233 op_sel:[0,0,1]
	v_fma_f32 v232, v91, v230, v71
	v_mul_f32_e32 v230, v227, v182
	v_fma_f32 v233, v92, v230, v72
	v_mul_f32_e32 v230, v227, v183
	v_fma_f32 v234, v93, v230, v73
	v_mov_b32_e32 v230, 0
	v_cvt_pk_fp8_f32 v230, v134, v232
	v_lshlrev_b32_e32 v186, 16, v231
	v_and_b32_e32 v231, 0xffff0000, v231
	v_mul_f32_e32 v134, v227, v184
	v_mul_f32_e32 v232, v227, v185
	v_cvt_pk_fp8_f32 v230, v233, v234 op_sel:[0,0,1]
	v_fma_f32 v134, v94, v134, v66
	v_fma_f32 v232, v95, v232, v67
	v_mul_f32_e32 v233, v227, v186
	v_mul_f32_e32 v227, v227, v231
	v_mov_b32_e32 v231, 0
	v_cvt_pk_fp8_f32 v231, v134, v232
	v_fma_f32 v233, v96, v233, v68
	v_fma_f32 v227, v97, v227, v69
	s_waitcnt vmcnt(9)
	v_and_b32_e32 v134, 0xffff0000, v216
	v_cvt_pk_fp8_f32 v231, v233, v227 op_sel:[0,0,1]
	v_lshl_add_u64 v[232:233], v[148:149], 0, s[28:29]
	s_waitcnt vmcnt(8)
	v_lshlrev_b32_e32 v227, 16, v220
	v_and_b32_e32 v220, 0xffff0000, v220
	global_store_dwordx4 v[232:233], v[228:231], off
	v_lshlrev_b32_e32 v232, 16, v217
	v_and_b32_e32 v233, 0xffff0000, v217
	v_lshlrev_b32_e32 v231, 16, v216
	s_waitcnt lgkmcnt(2)
	v_mul_f32_e32 v216, v226, v227
	v_lshlrev_b32_e32 v228, 16, v221
	v_fma_f32 v217, v82, v216, v78
	v_mul_f32_e32 v216, v226, v220
	v_and_b32_e32 v221, 0xffff0000, v221
	v_lshlrev_b32_e32 v234, 16, v218
	v_and_b32_e32 v235, 0xffff0000, v218
	v_fma_f32 v218, v83, v216, v79
	v_mul_f32_e32 v216, v226, v228
	v_fma_f32 v220, v84, v216, v80
	v_mul_f32_e32 v216, v226, v221
	v_fma_f32 v221, v85, v216, v81
	v_mov_b32_e32 v216, 0
	v_cvt_pk_fp8_f32 v216, v217, v218
	v_lshlrev_b32_e32 v229, 16, v222
	v_and_b32_e32 v222, 0xffff0000, v222
	v_mul_f32_e32 v217, v226, v229
	v_lshlrev_b32_e32 v230, 16, v223
	v_fma_f32 v218, v86, v217, v74
	v_mul_f32_e32 v217, v226, v222
	v_and_b32_e32 v223, 0xffff0000, v223
	v_cvt_pk_fp8_f32 v216, v220, v221 op_sel:[0,0,1]
	v_fma_f32 v220, v87, v217, v75
	v_mul_f32_e32 v217, v226, v230
	v_fma_f32 v221, v88, v217, v76
	v_mul_f32_e32 v217, v226, v223
	v_fma_f32 v222, v89, v217, v77
	v_mov_b32_e32 v217, 0
	v_cvt_pk_fp8_f32 v217, v218, v220
	v_mul_f32_e32 v218, v226, v231
	v_fma_f32 v220, v90, v218, v70
	v_mul_f32_e32 v218, v226, v134
	v_cvt_pk_fp8_f32 v217, v221, v222 op_sel:[0,0,1]
	v_fma_f32 v221, v91, v218, v71
	v_mul_f32_e32 v218, v226, v232
	v_fma_f32 v222, v92, v218, v72
	v_mul_f32_e32 v218, v226, v233
	v_fma_f32 v223, v93, v218, v73
	v_mov_b32_e32 v218, 0
	v_cvt_pk_fp8_f32 v218, v220, v221
	v_lshlrev_b32_e32 v176, 16, v219
	v_and_b32_e32 v219, 0xffff0000, v219
	v_mul_f32_e32 v220, v226, v234
	v_mul_f32_e32 v221, v226, v235
	v_mul_f32_e32 v219, v226, v219
	v_cvt_pk_fp8_f32 v218, v222, v223 op_sel:[0,0,1]
	v_fma_f32 v220, v94, v220, v66
	v_fma_f32 v221, v95, v221, v67
	v_fma_f32 v223, v97, v219, v69
	v_mov_b32_e32 v219, 0
	v_cvt_pk_fp8_f32 v219, v220, v221
	v_mul_f32_e32 v222, v226, v176
	v_fma_f32 v222, v96, v222, v68
	v_lshl_add_u64 v[220:221], v[148:149], 0, s[12:13]
	v_cvt_pk_fp8_f32 v219, v222, v223 op_sel:[0,0,1]
	s_waitcnt vmcnt(8)
	v_lshlrev_b32_e32 v222, 16, v209
	v_and_b32_e32 v223, 0xffff0000, v209
	v_lshlrev_b32_e32 v226, 16, v210
	global_store_dwordx4 v[220:221], v[216:219], off
	v_lshlrev_b32_e32 v220, 16, v208
	v_and_b32_e32 v221, 0xffff0000, v208
	s_waitcnt vmcnt(8)
	v_lshlrev_b32_e32 v216, 16, v212
	v_and_b32_e32 v212, 0xffff0000, v212
	s_waitcnt lgkmcnt(1)
	v_mul_f32_e32 v208, v225, v216
	v_lshlrev_b32_e32 v217, 16, v213
	v_fma_f32 v209, v82, v208, v78
	v_mul_f32_e32 v208, v225, v212
	v_and_b32_e32 v213, 0xffff0000, v213
	v_and_b32_e32 v227, 0xffff0000, v210
	v_fma_f32 v210, v83, v208, v79
	v_mul_f32_e32 v208, v225, v217
	v_fma_f32 v212, v84, v208, v80
	v_mul_f32_e32 v208, v225, v213
	v_fma_f32 v213, v85, v208, v81
	v_mov_b32_e32 v208, 0
	v_cvt_pk_fp8_f32 v208, v209, v210
	v_lshlrev_b32_e32 v218, 16, v214
	v_and_b32_e32 v214, 0xffff0000, v214
	v_mul_f32_e32 v209, v225, v218
	v_lshlrev_b32_e32 v219, 16, v215
	v_fma_f32 v210, v86, v209, v74
	v_mul_f32_e32 v209, v225, v214
	v_and_b32_e32 v215, 0xffff0000, v215
	v_cvt_pk_fp8_f32 v208, v212, v213 op_sel:[0,0,1]
	v_fma_f32 v212, v87, v209, v75
	v_mul_f32_e32 v209, v225, v219
	v_fma_f32 v213, v88, v209, v76
	v_mul_f32_e32 v209, v225, v215
	v_fma_f32 v214, v89, v209, v77
	v_mov_b32_e32 v209, 0
	v_cvt_pk_fp8_f32 v209, v210, v212
	v_mul_f32_e32 v210, v225, v220
	v_fma_f32 v212, v90, v210, v70
	v_mul_f32_e32 v210, v225, v221
	v_cvt_pk_fp8_f32 v209, v213, v214 op_sel:[0,0,1]
	v_fma_f32 v213, v91, v210, v71
	v_mul_f32_e32 v210, v225, v222
	v_fma_f32 v214, v92, v210, v72
	v_mul_f32_e32 v210, v225, v223
	v_fma_f32 v215, v93, v210, v73
	v_mov_b32_e32 v210, 0
	v_cvt_pk_fp8_f32 v210, v212, v213
	v_lshlrev_b32_e32 v228, 16, v211
	v_and_b32_e32 v211, 0xffff0000, v211
	v_mul_f32_e32 v212, v225, v226
	v_mul_f32_e32 v213, v225, v227
	v_mul_f32_e32 v211, v225, v211
	v_cvt_pk_fp8_f32 v210, v214, v215 op_sel:[0,0,1]
	v_fma_f32 v212, v94, v212, v66
	v_fma_f32 v213, v95, v213, v67
	v_fma_f32 v215, v97, v211, v69
	v_mov_b32_e32 v211, 0
	v_cvt_pk_fp8_f32 v211, v212, v213
	v_mul_f32_e32 v214, v225, v228
	v_fma_f32 v214, v96, v214, v68
	s_or_b32 s12, s28, 0x800
	v_cvt_pk_fp8_f32 v211, v214, v215 op_sel:[0,0,1]
	v_lshl_add_u64 v[212:213], v[148:149], 0, s[12:13]
	s_waitcnt vmcnt(7)
	v_lshlrev_b32_e32 v214, 16, v201
	v_and_b32_e32 v215, 0xffff0000, v201
	global_store_dwordx4 v[212:213], v[208:211], off
	v_lshlrev_b32_e32 v212, 16, v200
	v_and_b32_e32 v213, 0xffff0000, v200
	s_waitcnt vmcnt(7)
	v_lshlrev_b32_e32 v208, 16, v204
	v_and_b32_e32 v204, 0xffff0000, v204
	s_waitcnt lgkmcnt(0)
	v_mul_f32_e32 v200, v224, v208
	v_lshlrev_b32_e32 v209, 16, v205
	v_fma_f32 v201, v82, v200, v78
	v_mul_f32_e32 v200, v224, v204
	v_and_b32_e32 v205, 0xffff0000, v205
	v_lshlrev_b32_e32 v216, 16, v202
	v_and_b32_e32 v217, 0xffff0000, v202
	v_fma_f32 v202, v83, v200, v79
	v_mul_f32_e32 v200, v224, v209
	v_fma_f32 v204, v84, v200, v80
	v_mul_f32_e32 v200, v224, v205
	v_fma_f32 v205, v85, v200, v81
	v_mov_b32_e32 v200, 0
	v_cvt_pk_fp8_f32 v200, v201, v202
	v_lshlrev_b32_e32 v210, 16, v206
	v_and_b32_e32 v206, 0xffff0000, v206
	v_mul_f32_e32 v201, v224, v210
	v_lshlrev_b32_e32 v211, 16, v207
	v_fma_f32 v202, v86, v201, v74
	v_mul_f32_e32 v201, v224, v206
	v_and_b32_e32 v207, 0xffff0000, v207
	v_cvt_pk_fp8_f32 v200, v204, v205 op_sel:[0,0,1]
	v_fma_f32 v204, v87, v201, v75
	v_mul_f32_e32 v201, v224, v211
	v_fma_f32 v205, v88, v201, v76
	v_mul_f32_e32 v201, v224, v207
	v_fma_f32 v206, v89, v201, v77
	v_mov_b32_e32 v201, 0
	v_cvt_pk_fp8_f32 v201, v202, v204
	v_mul_f32_e32 v202, v224, v212
	v_fma_f32 v204, v90, v202, v70
	v_mul_f32_e32 v202, v224, v213
	v_cvt_pk_fp8_f32 v201, v205, v206 op_sel:[0,0,1]
	v_fma_f32 v205, v91, v202, v71
	v_mul_f32_e32 v202, v224, v214
	v_fma_f32 v206, v92, v202, v72
	v_mul_f32_e32 v202, v224, v215
	v_fma_f32 v207, v93, v202, v73
	v_mov_b32_e32 v202, 0
	v_cvt_pk_fp8_f32 v202, v204, v205
	v_lshlrev_b32_e32 v218, 16, v203
	v_and_b32_e32 v203, 0xffff0000, v203
	v_mul_f32_e32 v204, v224, v216
	v_mul_f32_e32 v205, v224, v217
	v_mul_f32_e32 v203, v224, v203
	v_cvt_pk_fp8_f32 v202, v206, v207 op_sel:[0,0,1]
	v_fma_f32 v204, v94, v204, v66
	v_fma_f32 v205, v95, v205, v67
	v_fma_f32 v207, v97, v203, v69
	v_mov_b32_e32 v203, 0
	v_cvt_pk_fp8_f32 v203, v204, v205
	v_mul_f32_e32 v206, v224, v218
	v_fma_f32 v206, v96, v206, v68
	s_or_b32 s12, s28, 0xc00
	v_cvt_pk_fp8_f32 v203, v206, v207 op_sel:[0,0,1]
	s_add_u32 s28, s28, 0x1000
	s_addc_u32 s29, s29, 0
	v_lshl_add_u64 v[204:205], v[148:149], 0, s[12:13]
	global_store_dwordx4 v[204:205], v[200:203], off
	s_add_i32 s8, s8, s84
	s_add_i32 s9, s9, s84
	s_cmpk_gt_i32 s8, 0xff
	s_mov_b64 s[38:39], -1
	s_cbranch_scc1 .LBB0_1559
	s_mov_b32 s26, s24
	s_branch .LBB0_1393
